# speedup vs baseline: 1.0247x; 1.0032x over previous
; __device__ __forceinline__ int crow(int r, int hi) { return (r & 3) + 8 * (r >> 2) + 4 * hi; }
; __device__ __forceinline__ float max3f(float a, float b, float c) { float r; asm("v_max3_f32 %0, %1, %2, %3" : "=v"(r) : "v"(a), "v"(b), "v"(c)); return r; }
; __device__ __forceinline__ float ex2(float x) { return __builtin_amdgcn_exp2f(x); }
; #define ATT_LWAIT() asm volatile("s_waitcnt lgkmcnt(0)" ::: "memory")
; template <int MODE> ...
;     ...
;                 asm volatile("s_nop 15\n\ts_nop 7" : "+v"(p0), "+v"(p1));
;                 float rm;
;                 { float a = max3f(p0[0], p0[1], p1[0]), b = max3f(p0[2], p0[3], p1[1]); a = max3f(a, p1[2], p1[3]);
; #pragma unroll
;                   for (int r = 4; r < 16; r += 4) { a = max3f(a, p0[r], p0[r + 1]); b = max3f(b, p0[r + 2], p0[r + 3]); a = max3f(a, p1[r], p1[r + 1]); b = max3f(b, p1[r + 2], p1[r + 3]); }
;                   rm = max3f(a, b, b); }
;                 { auto rr = __builtin_amdgcn_permlane32_swap(__float_as_uint(rm), __float_as_uint(rm), false, false); rm = max3f(__uint_as_float(rr[0]), __uint_as_float(rr[1]), __uint_as_float(rr[1])); }
;                 if (__any(rm > mhat + 6.0f)) {
;                     const float mnew = fmaxf(mhat, rm), f = ex2(mhat - mnew); mhat = mnew; lsum *= f;
;                     if (hi == 0) wsf[r32] = f;
;                     ATT_LWAIT();
; #pragma unroll
;                     for (int r = 0; r < 16; ++r) { const float fr_ = wsf[crow(r, hi)];
; #pragma unroll
;                         for (int db = 0; db < NDB; ++db) o[db][r] *= fr_; }
.LBB0_201:
	s_nop 11
	s_nop 0
	v_max3_f32 v84, v50, v51, v34
	v_max3_f32 v85, v52, v53, v35
	v_max3_f32 v84, v84, v36, v37
	v_max3_f32 v85, v85, v56, v57
	v_max3_f32 v84, v84, v54, v55
	v_max3_f32 v85, v85, v40, v41
	v_max3_f32 v84, v84, v38, v39
	v_max3_f32 v85, v85, v60, v61
	v_max3_f32 v84, v84, v58, v59
	v_max3_f32 v85, v85, v44, v45
	v_max3_f32 v84, v84, v42, v43
	v_max3_f32 v85, v85, v64, v65
	v_max3_f32 v84, v84, v62, v63
	v_max3_f32 v85, v85, v48, v49
	v_max3_f32 v84, v84, v46, v47
	v_max3_f32 v84, v84, v85, v85
	v_mov_b32_e32 v85, v84
	s_nop 1
	v_permlane32_swap_b32_e32 v84, v85
	v_max3_f32 v84, v84, v85, v85
	v_add_f32_e32 v85, 0x40c00000, v0
	v_cmp_gt_f32_e32 vcc, v84, v85
	s_cbranch_vccz .LBB0_206
	v_max_f32_e32 v84, v84, v84
	v_max_f32_e32 v85, v0, v0
	v_max_f32_e32 v132, v85, v84
	v_sub_f32_e32 v0, v0, v132
	v_exp_f32_e32 v0, v0
	s_and_saveexec_b64 s[4:5], s[0:1]
	ds_write_b32 v103, v0
	s_or_b64 exec, exec, s[4:5]
	s_waitcnt lgkmcnt(0)
	ds_read_b128 v[84:87], v131 offset:96
	ds_read_b128 v[88:91], v131 offset:64
	ds_read_b128 v[92:95], v131
	ds_read_b128 v[134:137], v131 offset:32
	v_mul_f32_e32 v104, v104, v0
	s_waitcnt lgkmcnt(2)
	v_pk_mul_f32 v[12:13], v[12:13], v[90:91]
	v_pk_mul_f32 v[16:17], v[16:17], v[86:87]
	v_pk_mul_f32 v[14:15], v[14:15], v[84:85]
	v_pk_mul_f32 v[10:11], v[10:11], v[88:89]
	s_waitcnt lgkmcnt(0)
	v_pk_mul_f32 v[8:9], v[8:9], v[136:137]
	v_pk_mul_f32 v[6:7], v[6:7], v[134:135]
	v_pk_mul_f32 v[4:5], v[4:5], v[94:95]
	v_pk_mul_f32 v[2:3], v[2:3], v[92:93]
	v_pk_mul_f32 v[32:33], v[32:33], v[86:87]
	v_pk_mul_f32 v[30:31], v[30:31], v[84:85]
	v_pk_mul_f32 v[28:29], v[28:29], v[90:91]
	v_pk_mul_f32 v[26:27], v[26:27], v[88:89]
	v_pk_mul_f32 v[24:25], v[24:25], v[136:137]
	v_pk_mul_f32 v[22:23], v[22:23], v[134:135]
	v_pk_mul_f32 v[20:21], v[20:21], v[94:95]
	v_pk_mul_f32 v[18:19], v[18:19], v[92:93]
	s_branch .LBB0_207

; #define MK_TID(wave_) ((wave_) * 64 + MK_LANE())
; #define ALAS __attribute__((address_space(3)))
; #define tid MK_TID(wave)
; template <int MODE> ...
;     ...
;     int tid_ = MK_TID(wave_s); asm volatile("" : "+v"(tid_));
;     const int tid = tid_, lane = tid & 63, r32 = lane & 31, hi = lane >> 5;
;     const int wid = __builtin_amdgcn_readfirstlane(tid >> 6);
;     const int q0 = qb * 256, qw = q0 + 32 * wid;
;     const int thi = 4 * qb + 3, tlo = (MODE == 2) ? (qb ? 4 * qb - 2 : 0) : 0, n = thi - tlo + 1;
;     const unsigned lds0 = (unsigned)(uintptr_t)shm;
;     ALAS float* wsf = (ALAS float*)(shm + L_WS) + wid * 64;
;     ...
;     ATT_DMA_TILE(ATT_TILE_OF(0), 0, 0);
;     bf16x8 qr[ND0];
; #pragma unroll
;     for (int d0 = 0; d0 < ND0; ++d0) qr[d0] = *(const bf16x8*)(Qp + (size_t)(qw + r32) * pitchQ + d0 * 16 + hi * 8);
; __global__ void __launch_bounds__(NTHREADS, 2) mega_fwd(Params P) {
;     ...
;                 if (tid == 0) MISC[0] = atomicAdd(ctr, 1u);
;                 __syncthreads();
;                 const int item = (int)MISC[0];
;                 if (item >= 768) break;
;                 if (item < 256) {
;     ...
;                     const int qb = 31 - (item >> 3), h = item & 7;
;                     att::attn_unit<1>(QS + h * 128, 1024, KS + h * 128, 1024, VS + h * 128, 1024, OCAT + 1024 + h * 128, 2048, qb, 0.f, lds, wave);
;     ...
;                     __syncthreads();
;     ...
;                 } else {
;     ...
;                     const int i2 = item - 256, qb = 31 - (i2 >> 4), hm = i2 & 15, h = hm >> 1, m = hm & 1;
.LBB0_227:
	s_or_b64 exec, exec, s[0:1]
	v_mov_b32_e32 v0, s50
	s_waitcnt lgkmcnt(0)
	s_barrier
	ds_read_b32 v0, v0
	s_movk_i32 s0, 0x2ff
	s_waitcnt lgkmcnt(0)
	v_cmp_lt_i32_e32 vcc, s0, v0
	v_readfirstlane_b32 s16, v0
	s_mov_b64 s[0:1], -1
	s_cbranch_vccnz .LBB0_222
	s_cmpk_lt_i32 s16, 0x200
	s_cbranch_scc0 .LBB0_266
	s_mov_b32 s0, s16
	s_lshr_b32 s10, s0, 4
	s_lshl_b32 s0, s16, 6
	s_and_b32 s18, s0, 0x380
	s_sub_i32 s6, 31, s10
	s_and_b32 s19, s16, 1
	s_lshl_b32 s4, s18, 1
	s_add_u32 s0, s48, s4
	s_addc_u32 s1, s49, 0
	s_lshl_b32 s5, s19, 7
	s_add_u32 s0, s0, s5
	s_addc_u32 s1, s1, 0
	v_readlane_b32 s7, v255, 4
	s_add_u32 s7, s7, s4
	v_readlane_b32 s11, v255, 5
	s_addc_u32 s11, s11, 0
	s_add_u32 s12, s7, s5
	s_addc_u32 s13, s11, 0
	v_readlane_b32 s5, v255, 0
	v_mbcnt_lo_u32_b32 v0, -1, 0
	v_mbcnt_hi_u32_b32 v0, -1, v0
	s_add_u32 s22, s5, s4
	v_add_u32_e32 v4, s3, v0
	v_readlane_b32 s4, v255, 1
	s_addc_u32 s23, s4, 0
	v_readfirstlane_b32 s7, v4
	s_ashr_i32 s20, s7, 6
	v_and_b32_e32 v134, 63, v4
	s_lshl_b32 s4, s20, 3
	v_lshlrev_b32_e32 v0, 11, v134
	s_ashr_i32 s5, s4, 31
	v_lshl_add_u64 v[2:3], s[12:13], 0, v[0:1]
	s_lshl_b64 s[28:29], s[4:5], 1
	s_lshl_b32 s21, s20, 10
	v_lshl_add_u64 v[2:3], v[2:3], 0, s[28:29]
	s_add_i32 s26, s21, 0
	s_mov_b32 s4, m0
	s_mov_b32 m0, s26
	s_nop 0
	global_load_lds_dwordx4 v[2:3], off
	s_mov_b32 m0, s4
	s_lshl_b32 s4, s20, 4
	v_bfe_u32 v0, v4, 2, 4
	v_and_or_b32 v5, s4, 48, v0
	s_ashr_i32 s4, s7, 3
	s_andn2_b32 s4, s4, 31
	v_lshlrev_b32_e32 v0, 11, v5
	s_ashr_i32 s5, s4, 31
	v_lshlrev_b32_e32 v135, 3, v4
	v_lshl_add_u64 v[2:3], s[22:23], 0, v[0:1]
	s_lshl_b64 s[30:31], s[4:5], 1
	v_and_b32_e32 v194, 24, v135
	v_lshl_add_u64 v[2:3], v[2:3], 0, s[30:31]
	v_lshlrev_b32_e32 v0, 1, v194
	s_add_i32 s11, 0, 0x8000
	v_lshl_add_u64 v[2:3], v[2:3], 0, v[0:1]
	s_add_i32 s4, s21, s11
	s_mov_b32 s5, m0
	s_mov_b32 m0, s4
	s_nop 0
	global_load_lds_dwordx4 v[2:3], off
	s_mov_b32 m0, s5
	s_add_i32 s14, 0, 0xa000
	v_lshl_add_u64 v[2:3], v[2:3], 0, s[92:93]
	s_add_i32 s21, s21, s14
	s_mov_b32 s4, m0
	s_mov_b32 m0, s21
	s_nop 0
	global_load_lds_dwordx4 v[2:3], off
	s_mov_b32 m0, s4
	s_lshl_b32 s17, s20, 5
	s_lshl_b32 s4, s6, 8
	v_and_b32_e32 v136, 31, v4
	s_add_i32 s17, s17, s4
	v_or_b32_e32 v130, s17, v136
	v_ashrrev_i32_e32 v131, 31, v130
	v_bfe_u32 v137, v4, 5, 1
	v_lshlrev_b64 v[2:3], 11, v[130:131]
	v_lshl_add_u64 v[2:3], s[0:1], 0, v[2:3]
	v_lshlrev_b32_e32 v128, 4, v137
	v_mov_b32_e32 v129, v1
	v_lshl_add_u64 v[2:3], v[2:3], 0, v[128:129]
	global_load_dwordx4 v[124:127], v[2:3], off
	global_load_dwordx4 v[120:123], v[2:3], off offset:32
	global_load_dwordx4 v[116:119], v[2:3], off offset:64
	global_load_dwordx4 v[112:115], v[2:3], off offset:96
	s_and_b32 s15, s7, 0x3fffffc0
	s_lshl_b32 s0, s15, 2
	s_add_i32 s21, s0, 0
	s_add_i32 s21, s21, 0x14000
	s_cmp_gt_i32 s20, 3
	s_cselect_b64 s[4:5], -1, 0
	s_cmp_lt_i32 s20, 4
	s_cselect_b64 s[6:7], -1, 0
	s_add_u32 s12, s12, s28
	s_addc_u32 s13, s13, s29
	s_add_u32 s0, s22, s30
	s_addc_u32 s1, s23, s31
	v_lshl_add_u64 v[132:133], s[0:1], 0, v[0:1]
	v_lshlrev_b32_e32 v0, 1, v4
	v_and_b32_e32 v200, 32, v0
	v_lshlrev_b32_e32 v2, 4, v4
	v_add3_u32 v0, 0, v200, v194
	v_lshlrev_b32_e32 v210, 8, v137
	v_and_b32_e32 v211, 0xc0, v2
	v_add3_u32 v143, v0, v210, v211
	v_lshlrev_b32_e32 v129, 10, v137
	v_lshlrev_b32_e32 v0, 4, v136
	s_lshl_b32 s10, s10, 2
	v_add3_u32 v144, 0, v129, v0
	s_sub_i32 s30, 0, s10
	v_or_b32_e32 v0, v210, v211
	v_readlane_b32 s10, v254, 6
	s_waitcnt vmcnt(0) lgkmcnt(0)
	s_barrier
; #define ATT_WAIT_BAR() asm volatile("s_waitcnt vmcnt(0) lgkmcnt(0)\n\ts_barrier" ::: "memory")
; template <int MODE> ...
;     ...
;     f32x16 o[NDB];
; #pragma unroll
;     for (int db = 0; db < NDB; ++db) o[db] = f32x16{};
;     float mhat = -1e30f, lsum = 0.f, Rp = 0.f;
;     u32x4 pw0 = {}, pw1 = {}, pw2 = {}, pw3 = {};
;     const bool late = (MODE != 1) && wid >= 4; bool pend = false; int pvslot = 0;
;     constexpr int NVB = NDB * 4 / 8;
;     ...
;     ATT_WAIT_BAR();
; #pragma unroll
;     for (int d0 = 0; d0 < ND0; ++d0) asm volatile("" : "+v"(qr[d0]));
;     for (int i = 0; i < n; ++i) {
;         const int t = ATT_TILE_OF(i), slot = i & 1, vslot = i % 3;
;         if (i + 1 < n) ATT_DMA_TILE(ATT_TILE_OF(i + 1), slot ^ 1, (i + 1) % 3);
;         if (late && pend) { ATT_PV(pvslot); pend = false; }
;         bool active, full;
;         if (MODE == 0) { active = 64 * t <= qw + 31; full = 64 * t + 63 <= qw; }
;         else if (MODE == 1) { active = 64 * t <= qw + 30; full = 64 * t + 63 < qw; }
;         else { active = (64 * t <= qw + 31) && (64 * t + 63 >= qw - 127); full = (64 * t + 63 <= qw) && (64 * t >= qw - 96); }
;         if (active) {
;             const lds_cptr kp = (lds_cptr)shm + L_K + slot * KSLOT + hi * 1024 + r32 * 16;
	v_mov_b32_e32 v14, v1
	v_mov_b32_e32 v15, v1
	v_add_u32_e32 v146, s10, v0
	v_readlane_b32 s10, v254, 7
	v_or_b32_e32 v145, 64, v5
	v_add_u32_e32 v166, s14, v0
	v_add_u32_e32 v215, s10, v0
	v_readlane_b32 s10, v254, 8
	v_add_u32_e32 v180, s51, v0
	v_add_u32_e32 v181, s33, v0
	v_add_u32_e32 v214, s10, v0
	v_readlane_b32 s10, v254, 9
	v_add_u32_e32 v182, s11, v0
	v_mov_b32_e32 v2, v1
	v_add_u32_e32 v201, s10, v0
	v_readlane_b32 s10, v254, 10
	v_mov_b32_e32 v3, v1
	v_mov_b32_e32 v4, v1
	v_add_u32_e32 v252, s10, v0
	v_readlane_b32 s10, v254, 11
	v_mov_b32_e32 v5, v1
	v_mov_b32_e32 v6, v1
	v_add_u32_e32 v152, s10, v0
	v_readlane_b32 s10, v254, 12
	v_mov_b32_e32 v7, v1
	v_mov_b32_e32 v8, v1
	v_add_u32_e32 v153, s10, v0
	v_readlane_b32 s10, v254, 13
	v_mov_b32_e32 v9, v1
	v_mov_b32_e32 v10, v1
	v_add_u32_e32 v154, s10, v0
	v_readlane_b32 s10, v254, 14
	v_mov_b32_e32 v11, v1
	v_mov_b32_e32 v12, v1
	v_add_u32_e32 v155, s10, v0
	v_readlane_b32 s10, v254, 15
	v_mov_b32_e32 v13, v1
	s_mov_b32 s25, 1
	v_add_u32_e32 v156, s10, v0
	v_readlane_b32 s10, v254, 16
	s_or_b32 s27, s17, 31
	v_cmp_gt_u32_e64 s[0:1], 32, v134
	v_add_u32_e32 v157, s10, v0
	v_readlane_b32 s10, v254, 17
	v_lshl_add_u32 v131, v136, 2, s21
	s_mov_b32 s28, 0
	v_add_u32_e32 v162, s10, v0
	v_readlane_b32 s10, v254, 18
	s_add_i32 s31, s26, 0xc000
	v_or_b32_e32 v147, v194, v200
	v_add_u32_e32 v163, s10, v0
	v_readlane_b32 s10, v254, 19
	v_mov_b32_e32 v142, 0
	v_mov_b32_e32 v185, 0xf149f2ca
	v_add_u32_e32 v164, s10, v0
	v_readlane_b32 s10, v254, 20
	s_movk_i32 s29, 0xff81
	v_mov_b32_e32 v84, 0
	v_add_u32_e32 v165, s10, v0
	v_readlane_b32 s10, v255, 57
	v_mov_b32_e32 v85, 0
	v_mov_b32_e32 v86, 0
	v_add_u32_e32 v167, s10, v0
	v_readlane_b32 s10, v255, 58
	v_mov_b32_e32 v87, 0
	v_mov_b32_e32 v92, 0
	v_add_u32_e32 v168, s10, v0
	v_readlane_b32 s10, v255, 59
	v_mov_b32_e32 v93, 0
	v_mov_b32_e32 v94, 0
	v_add_u32_e32 v169, s10, v0
	v_readlane_b32 s10, v255, 60
	v_mov_b32_e32 v95, 0
	v_mov_b32_e32 v80, 0
	v_add_u32_e32 v170, s10, v0
	v_readlane_b32 s10, v255, 61
	v_mov_b32_e32 v81, 0
	v_mov_b32_e32 v82, 0
	v_add_u32_e32 v171, s10, v0
	v_readlane_b32 s10, v255, 62
	v_mov_b32_e32 v83, 0
	v_mov_b32_e32 v88, 0
	v_add_u32_e32 v172, s10, v0
	v_readlane_b32 s10, v255, 63
	v_mov_b32_e32 v89, 0
	v_mov_b32_e32 v90, 0
	v_add_u32_e32 v173, s10, v0
	v_readlane_b32 s10, v254, 0
	v_mov_b32_e32 v91, 0
	v_mov_b32_e32 v183, v130
	v_add_u32_e32 v174, s10, v0
	v_readlane_b32 s10, v254, 1
	s_mov_b32 s23, 0
	s_mov_b32 s22, 0
	v_add_u32_e32 v175, s10, v0
	v_readlane_b32 s10, v254, 2
	s_mov_b32 s24, 0
	s_waitcnt vmcnt(0)
	v_add_u32_e32 v176, s10, v0
	v_readlane_b32 s10, v254, 3
	s_nop 1
	v_add_u32_e32 v177, s10, v0
	v_readlane_b32 s10, v254, 4
	s_nop 1
	v_add_u32_e32 v178, s10, v0
	v_readlane_b32 s10, v254, 5
	s_nop 1
	v_add_u32_e32 v179, s10, v0
	v_mov_b32_e32 v0, v1
	v_mov_b64_e32 v[30:31], v[14:15]
	v_mov_b64_e32 v[46:47], v[14:15]
	v_mov_b64_e32 v[62:63], v[14:15]
	v_mov_b64_e32 v[78:79], v[14:15]
	s_mov_b64 s[10:11], 0
	v_mov_b64_e32 v[28:29], v[12:13]
	v_mov_b64_e32 v[26:27], v[10:11]
	v_mov_b64_e32 v[24:25], v[8:9]
	v_mov_b64_e32 v[22:23], v[6:7]
	v_mov_b64_e32 v[20:21], v[4:5]
	v_mov_b64_e32 v[18:19], v[2:3]
	v_mov_b64_e32 v[16:17], v[0:1]
	v_mov_b64_e32 v[44:45], v[12:13]
	v_mov_b64_e32 v[42:43], v[10:11]
	v_mov_b64_e32 v[40:41], v[8:9]
	v_mov_b64_e32 v[38:39], v[6:7]
	v_mov_b64_e32 v[36:37], v[4:5]
	v_mov_b64_e32 v[34:35], v[2:3]
	v_mov_b64_e32 v[32:33], v[0:1]
	v_mov_b64_e32 v[60:61], v[12:13]
	v_mov_b64_e32 v[58:59], v[10:11]
	v_mov_b64_e32 v[56:57], v[8:9]
	v_mov_b64_e32 v[54:55], v[6:7]
	v_mov_b64_e32 v[52:53], v[4:5]
	v_mov_b64_e32 v[50:51], v[2:3]
	v_mov_b64_e32 v[48:49], v[0:1]
	v_mov_b64_e32 v[76:77], v[12:13]
	v_mov_b64_e32 v[74:75], v[10:11]
	v_mov_b64_e32 v[72:73], v[8:9]
	v_mov_b64_e32 v[70:71], v[6:7]
	v_mov_b64_e32 v[68:69], v[4:5]
	v_mov_b64_e32 v[66:67], v[2:3]
	v_mov_b64_e32 v[64:65], v[0:1]

; __device__ __forceinline__ int crow(int r, int hi) { return (r & 3) + 8 * (r >> 2) + 4 * hi; }
; __device__ __forceinline__ float max3f(float a, float b, float c) { float r; asm("v_max3_f32 %0, %1, %2, %3" : "=v"(r) : "v"(a), "v"(b), "v"(c)); return r; }
; __device__ __forceinline__ float ex2(float x) { return __builtin_amdgcn_exp2f(x); }
; #define ATT_LWAIT() asm volatile("s_waitcnt lgkmcnt(0)" ::: "memory")
; template <int MODE> ...
;     ...
;                 asm volatile("s_nop 15\n\ts_nop 7" : "+v"(p0), "+v"(p1));
;                 float rm;
;                 { float a = max3f(p0[0], p0[1], p1[0]), b = max3f(p0[2], p0[3], p1[1]); a = max3f(a, p1[2], p1[3]);
; #pragma unroll
;                   for (int r = 4; r < 16; r += 4) { a = max3f(a, p0[r], p0[r + 1]); b = max3f(b, p0[r + 2], p0[r + 3]); a = max3f(a, p1[r], p1[r + 1]); b = max3f(b, p1[r + 2], p1[r + 3]); }
;                   rm = max3f(a, b, b); }
;                 { auto rr = __builtin_amdgcn_permlane32_swap(__float_as_uint(rm), __float_as_uint(rm), false, false); rm = max3f(__uint_as_float(rr[0]), __uint_as_float(rr[1]), __uint_as_float(rr[1])); }
;                 if (__any(rm > mhat + 6.0f)) {
;                     const float mnew = fmaxf(mhat, rm), f = ex2(mhat - mnew); mhat = mnew; lsum *= f;
;                     if (hi == 0) wsf[r32] = f;
;                     ATT_LWAIT();
; #pragma unroll
;                     for (int r = 0; r < 16; ++r) { const float fr_ = wsf[crow(r, hi)];
; #pragma unroll
;                         for (int db = 0; db < NDB; ++db) o[db][r] *= fr_; }
.LBB0_235:
	s_nop 11
	s_nop 0
	v_max3_f32 v0, v96, v97, v80
	v_max3_f32 v2, v98, v99, v81
	v_max3_f32 v0, v0, v82, v83
	v_max3_f32 v2, v2, v102, v103
	v_max3_f32 v0, v0, v100, v101
	v_max3_f32 v2, v2, v86, v87
	v_max3_f32 v0, v0, v84, v85
	v_max3_f32 v2, v2, v106, v107
	v_max3_f32 v0, v0, v104, v105
	v_max3_f32 v2, v2, v90, v91
	v_max3_f32 v0, v0, v88, v89
	v_max3_f32 v2, v2, v110, v111
	v_max3_f32 v0, v0, v108, v109
	v_max3_f32 v2, v2, v94, v95
	v_max3_f32 v0, v0, v92, v93
	v_max3_f32 v0, v0, v2, v2
	v_mov_b32_e32 v2, v0
	s_nop 1
	v_permlane32_swap_b32_e32 v0, v2
	v_max3_f32 v0, v0, v2, v2
	v_add_f32_e32 v2, 0x40c00000, v185
	v_cmp_gt_f32_e32 vcc, v0, v2
	s_cbranch_vccz .LBB0_240
	v_max_f32_e32 v0, v0, v0
	v_max_f32_e32 v2, v185, v185
	v_max_f32_e32 v184, v2, v0
	v_sub_f32_e32 v0, v185, v184
	v_exp_f32_e32 v0, v0
	s_and_saveexec_b64 s[14:15], s[0:1]
	ds_write_b32 v131, v0
	s_or_b64 exec, exec, s[14:15]
	v_mul_f32_e32 v142, v142, v0
	s_waitcnt lgkmcnt(0)
	v_add_u32_e32 v0, s21, v128
	ds_read_b128 v[2:5], v0
	ds_read_b128 v[6:9], v0 offset:32
	ds_read_b128 v[10:13], v0 offset:64
	ds_read_b128 v[190:193], v0 offset:96
	s_waitcnt lgkmcnt(3)
	v_pk_mul_f32 v[66:67], v[66:67], v[4:5]
	s_waitcnt lgkmcnt(2)
	v_pk_mul_f32 v[68:69], v[68:69], v[6:7]
	s_waitcnt lgkmcnt(1)
	v_pk_mul_f32 v[72:73], v[72:73], v[10:11]
	s_waitcnt lgkmcnt(0)
	v_pk_mul_f32 v[76:77], v[76:77], v[190:191]
	v_pk_mul_f32 v[78:79], v[78:79], v[192:193]
	v_pk_mul_f32 v[74:75], v[74:75], v[12:13]
	v_pk_mul_f32 v[70:71], v[70:71], v[8:9]
	v_pk_mul_f32 v[64:65], v[64:65], v[2:3]
	v_pk_mul_f32 v[60:61], v[60:61], v[190:191]
	v_pk_mul_f32 v[56:57], v[56:57], v[10:11]
	v_pk_mul_f32 v[52:53], v[52:53], v[6:7]
	v_pk_mul_f32 v[62:63], v[62:63], v[192:193]
	v_pk_mul_f32 v[58:59], v[58:59], v[12:13]
	v_pk_mul_f32 v[54:55], v[54:55], v[8:9]
	v_pk_mul_f32 v[50:51], v[50:51], v[4:5]
	v_pk_mul_f32 v[48:49], v[48:49], v[2:3]
	v_pk_mul_f32 v[44:45], v[44:45], v[190:191]
	v_pk_mul_f32 v[40:41], v[40:41], v[10:11]
	v_pk_mul_f32 v[36:37], v[36:37], v[6:7]
	v_pk_mul_f32 v[46:47], v[46:47], v[192:193]
	v_pk_mul_f32 v[42:43], v[42:43], v[12:13]
	v_pk_mul_f32 v[38:39], v[38:39], v[8:9]
	v_pk_mul_f32 v[34:35], v[34:35], v[4:5]
	v_pk_mul_f32 v[32:33], v[32:33], v[2:3]
	v_pk_mul_f32 v[28:29], v[28:29], v[190:191]
	v_pk_mul_f32 v[24:25], v[24:25], v[10:11]
	v_pk_mul_f32 v[20:21], v[20:21], v[6:7]
	v_pk_mul_f32 v[30:31], v[30:31], v[192:193]
	v_pk_mul_f32 v[26:27], v[26:27], v[12:13]
	v_pk_mul_f32 v[22:23], v[22:23], v[8:9]
	v_pk_mul_f32 v[18:19], v[18:19], v[4:5]
	v_pk_mul_f32 v[16:17], v[16:17], v[2:3]
	s_branch .LBB0_241

; __device__ __forceinline__ int crow(int r, int hi) { return (r & 3) + 8 * (r >> 2) + 4 * hi; }
; __device__ __forceinline__ float max3f(float a, float b, float c) { float r; asm("v_max3_f32 %0, %1, %2, %3" : "=v"(r) : "v"(a), "v"(b), "v"(c)); return r; }
; __device__ __forceinline__ float ex2(float x) { return __builtin_amdgcn_exp2f(x); }
; #define ATT_LWAIT() asm volatile("s_waitcnt lgkmcnt(0)" ::: "memory")
; template <int MODE> ...
;     ...
;                 asm volatile("s_nop 15\n\ts_nop 7" : "+v"(p0), "+v"(p1));
;                 float rm;
;                 { float a = max3f(p0[0], p0[1], p1[0]), b = max3f(p0[2], p0[3], p1[1]); a = max3f(a, p1[2], p1[3]);
; #pragma unroll
;                   for (int r = 4; r < 16; r += 4) { a = max3f(a, p0[r], p0[r + 1]); b = max3f(b, p0[r + 2], p0[r + 3]); a = max3f(a, p1[r], p1[r + 1]); b = max3f(b, p1[r + 2], p1[r + 3]); }
;                   rm = max3f(a, b, b); }
;                 { auto rr = __builtin_amdgcn_permlane32_swap(__float_as_uint(rm), __float_as_uint(rm), false, false); rm = max3f(__uint_as_float(rr[0]), __uint_as_float(rr[1]), __uint_as_float(rr[1])); }
;                 if (__any(rm > mhat + 6.0f)) {
;                     const float mnew = fmaxf(mhat, rm), f = ex2(mhat - mnew); mhat = mnew; lsum *= f;
;                     if (hi == 0) wsf[r32] = f;
;                     ATT_LWAIT();
; #pragma unroll
;                     for (int r = 0; r < 16; ++r) { const float fr_ = wsf[crow(r, hi)];
; #pragma unroll
;                         for (int db = 0; db < NDB; ++db) o[db][r] *= fr_; }
.LBB0_252:
	s_nop 11
	s_nop 0
	v_max3_f32 v0, v96, v97, v80
	v_max3_f32 v2, v98, v99, v81
	v_max3_f32 v0, v0, v82, v83
	v_max3_f32 v2, v2, v102, v103
	v_max3_f32 v0, v0, v100, v101
	v_max3_f32 v2, v2, v86, v87
	v_max3_f32 v0, v0, v84, v85
	v_max3_f32 v2, v2, v106, v107
	v_max3_f32 v0, v0, v104, v105
	v_max3_f32 v2, v2, v90, v91
	v_max3_f32 v0, v0, v88, v89
	v_max3_f32 v2, v2, v110, v111
	v_max3_f32 v0, v0, v108, v109
	v_max3_f32 v2, v2, v94, v95
	v_max3_f32 v0, v0, v92, v93
	v_max3_f32 v0, v0, v2, v2
	v_mov_b32_e32 v2, v0
	s_nop 1
	v_permlane32_swap_b32_e32 v0, v2
	v_max3_f32 v0, v0, v2, v2
	v_add_f32_e32 v2, 0x40c00000, v184
	v_cmp_gt_f32_e32 vcc, v0, v2
	s_cbranch_vccz .LBB0_256
	v_max_f32_e32 v0, v0, v0
	v_max_f32_e32 v2, v184, v184
	v_max_f32_e32 v3, v2, v0
	v_sub_f32_e32 v0, v184, v3
	v_exp_f32_e32 v0, v0
	s_and_saveexec_b64 s[12:13], s[0:1]
	ds_write_b32 v131, v0
	s_or_b64 exec, exec, s[12:13]
	v_mul_f32_e32 v142, v142, v0
	s_waitcnt lgkmcnt(0)
	v_add_u32_e32 v0, s21, v128
	ds_read_b128 v[4:7], v0
	ds_read_b128 v[8:11], v0 offset:32
	ds_read_b128 v[12:15], v0 offset:64
	ds_read_b128 v[112:115], v0 offset:96
	s_waitcnt lgkmcnt(3)
	v_pk_mul_f32 v[66:67], v[66:67], v[6:7]
	s_waitcnt lgkmcnt(2)
	v_pk_mul_f32 v[68:69], v[68:69], v[8:9]
	s_waitcnt lgkmcnt(1)
	v_pk_mul_f32 v[72:73], v[72:73], v[12:13]
	s_waitcnt lgkmcnt(0)
	v_pk_mul_f32 v[76:77], v[76:77], v[112:113]
	v_pk_mul_f32 v[78:79], v[78:79], v[114:115]
	v_pk_mul_f32 v[74:75], v[74:75], v[14:15]
	v_pk_mul_f32 v[70:71], v[70:71], v[10:11]
	v_pk_mul_f32 v[64:65], v[64:65], v[4:5]
	v_pk_mul_f32 v[60:61], v[60:61], v[112:113]
	v_pk_mul_f32 v[56:57], v[56:57], v[12:13]
	v_pk_mul_f32 v[52:53], v[52:53], v[8:9]
	v_pk_mul_f32 v[62:63], v[62:63], v[114:115]
	v_pk_mul_f32 v[58:59], v[58:59], v[14:15]
	v_pk_mul_f32 v[54:55], v[54:55], v[10:11]
	v_pk_mul_f32 v[50:51], v[50:51], v[6:7]
	v_pk_mul_f32 v[48:49], v[48:49], v[4:5]
	v_pk_mul_f32 v[44:45], v[44:45], v[112:113]
	v_pk_mul_f32 v[40:41], v[40:41], v[12:13]
	v_pk_mul_f32 v[36:37], v[36:37], v[8:9]
	v_pk_mul_f32 v[46:47], v[46:47], v[114:115]
	v_pk_mul_f32 v[42:43], v[42:43], v[14:15]
	v_pk_mul_f32 v[38:39], v[38:39], v[10:11]
	v_pk_mul_f32 v[34:35], v[34:35], v[6:7]
	v_pk_mul_f32 v[32:33], v[32:33], v[4:5]
	v_pk_mul_f32 v[28:29], v[28:29], v[112:113]
	v_pk_mul_f32 v[24:25], v[24:25], v[12:13]
	v_pk_mul_f32 v[20:21], v[20:21], v[8:9]
	v_pk_mul_f32 v[30:31], v[30:31], v[114:115]
	v_pk_mul_f32 v[26:27], v[26:27], v[14:15]
	v_pk_mul_f32 v[22:23], v[22:23], v[10:11]
	v_pk_mul_f32 v[18:19], v[18:19], v[6:7]
	v_pk_mul_f32 v[16:17], v[16:17], v[4:5]
	s_branch .LBB0_257

; #define MK_TID(wave_) ((wave_) * 64 + MK_LANE())
; #define ALAS __attribute__((address_space(3)))
; #define tid MK_TID(wave)
; template <int MODE> ...
;     ...
;     int tid_ = MK_TID(wave_s); asm volatile("" : "+v"(tid_));
;     const int tid = tid_, lane = tid & 63, r32 = lane & 31, hi = lane >> 5;
;     const int wid = __builtin_amdgcn_readfirstlane(tid >> 6);
;     const int q0 = qb * 256, qw = q0 + 32 * wid;
;     const int thi = 4 * qb + 3, tlo = (MODE == 2) ? (qb ? 4 * qb - 2 : 0) : 0, n = thi - tlo + 1;
;     const unsigned lds0 = (unsigned)(uintptr_t)shm;
;     ALAS float* wsf = (ALAS float*)(shm + L_WS) + wid * 64;
;     ...
;     ATT_DMA_TILE(ATT_TILE_OF(0), 0, 0);
;     bf16x8 qr[ND0];
; #pragma unroll
;     for (int d0 = 0; d0 < ND0; ++d0) qr[d0] = *(const bf16x8*)(Qp + (size_t)(qw + r32) * pitchQ + d0 * 16 + hi * 8);
;     f32x16 o[NDB];
; #pragma unroll
;     for (int db = 0; db < NDB; ++db) o[db] = f32x16{};
;     float mhat = -1e30f, lsum = 0.f, Rp = 0.f;
;     u32x4 pw0 = {}, pw1 = {}, pw2 = {}, pw3 = {};
;     const bool late = (MODE != 1) && wid >= 4; bool pend = false; int pvslot = 0;
; __global__ void __launch_bounds__(NTHREADS, 2) mega_fwd(Params P) {
;     ...
;                     const int qb = 31 - (item >> 3), h = item & 7;
;                     att::attn_unit<1>(QS + h * 128, 1024, KS + h * 128, 1024, VS + h * 128, 1024, OCAT + 1024 + h * 128, 2048, qb, 0.f, lds, wave);
.LBB0_266:
	s_and_b64 vcc, exec, s[0:1]
	s_cbranch_vccz .LBB0_221
	s_addk_i32 s16, 0xfe00
	s_lshl_b32 s0, s16, 7
	s_ashr_i32 s24, s16, 3
	s_and_b32 s15, s0, 0x380
	s_sub_i32 s20, 31, s24
	s_lshl_b32 s6, s15, 1
	v_readlane_b32 s0, v255, 6
	s_add_u32 s0, s0, s6
	v_readlane_b32 s1, v255, 7
	s_addc_u32 s1, s1, 0
	v_readlane_b32 s4, v255, 8
	s_add_u32 s4, s4, s6
	v_readlane_b32 s5, v255, 9
	s_addc_u32 s5, s5, 0
	v_readlane_b32 s7, v255, 10
	s_add_u32 s6, s7, s6
	v_readlane_b32 s7, v255, 11
	v_mbcnt_lo_u32_b32 v0, -1, 0
	v_mbcnt_hi_u32_b32 v0, -1, v0
	s_addc_u32 s7, s7, 0
	v_add_u32_e32 v6, s3, v0
	s_lshl_b32 s14, s20, 8
	v_readfirstlane_b32 s17, v6
	v_and_b32_e32 v132, 63, v6
	s_ashr_i32 s16, s17, 6
	s_or_b32 s12, s14, 0xc0
	v_or_b32_e32 v0, s12, v132
	s_lshl_b32 s10, s16, 3
	v_lshlrev_b64 v[2:3], 11, v[0:1]
	s_ashr_i32 s11, s10, 31
	v_lshl_add_u64 v[2:3], s[4:5], 0, v[2:3]
	s_lshl_b64 s[10:11], s[10:11], 1
	s_lshl_b32 s19, s16, 10
	v_lshl_add_u64 v[2:3], v[2:3], 0, s[10:11]
	s_add_i32 s18, s19, 0
	s_mov_b32 s13, m0
	s_mov_b32 m0, s18
	s_nop 0
	global_load_lds_dwordx4 v[2:3], off
	s_mov_b32 m0, s13
	s_add_i32 s13, s18, 0x2000
	v_lshl_add_u64 v[2:3], v[2:3], 0, s[92:93]
	s_mov_b32 s21, m0
	s_mov_b32 m0, s13
	s_nop 0
	global_load_lds_dwordx4 v[2:3], off
	s_mov_b32 m0, s21
	s_lshl_b32 s13, s16, 4
	v_bfe_u32 v0, v6, 2, 4
	v_and_or_b32 v136, s13, 48, v0
	v_or_b32_e32 v0, s12, v136
	s_ashr_i32 s12, s17, 3
	s_andn2_b32 s12, s12, 31
	v_lshlrev_b64 v[2:3], 11, v[0:1]
	s_ashr_i32 s13, s12, 31
	v_lshlrev_b32_e32 v133, 3, v6
	v_lshl_add_u64 v[2:3], s[6:7], 0, v[2:3]
	s_lshl_b64 s[12:13], s[12:13], 1
	v_and_b32_e32 v7, 24, v133
	v_lshl_add_u64 v[2:3], v[2:3], 0, s[12:13]
	v_lshlrev_b32_e32 v0, 1, v7
	s_lshl_b32 s25, s16, 5
	v_lshl_add_u64 v[2:3], v[2:3], 0, v[0:1]
	s_add_i32 s26, 0, 0x8000
	v_and_b32_e32 v134, 31, v6
	s_add_i32 s21, s19, s26
	s_mov_b32 s22, m0
	s_mov_b32 m0, s21
	s_nop 0
	global_load_lds_dwordx4 v[2:3], off
	s_mov_b32 m0, s22
	v_lshl_add_u64 v[2:3], v[2:3], 0, s[92:93]
	s_add_i32 s27, 0, 0xa000
	s_add_i32 s14, s25, s14
	s_add_i32 s19, s19, s27
	s_mov_b32 s21, m0
	s_mov_b32 m0, s19
	s_nop 0
	global_load_lds_dwordx4 v[2:3], off
	s_mov_b32 m0, s21
	v_or_b32_e32 v2, s14, v134
	v_ashrrev_i32_e32 v3, 31, v2
	v_bfe_u32 v135, v6, 5, 1
	v_lshlrev_b64 v[2:3], 11, v[2:3]
	v_lshl_add_u64 v[2:3], s[0:1], 0, v[2:3]
	v_lshlrev_b32_e32 v4, 4, v135
	v_mov_b32_e32 v5, v1
	v_lshl_add_u64 v[2:3], v[2:3], 0, v[4:5]
	global_load_dwordx4 v[98:101], v[2:3], off
	global_load_dwordx4 v[102:105], v[2:3], off offset:32
	global_load_dwordx4 v[106:109], v[2:3], off offset:64
	global_load_dwordx4 v[110:113], v[2:3], off offset:96
	global_load_dwordx4 v[114:117], v[2:3], off offset:128
	global_load_dwordx4 v[118:121], v[2:3], off offset:160
	global_load_dwordx4 v[122:125], v[2:3], off offset:192
	global_load_dwordx4 v[126:129], v[2:3], off offset:224
	s_lshl_b32 s20, s20, 2
	s_add_i32 s20, s20, 4
	s_add_u32 s10, s4, s10
	s_addc_u32 s11, s5, s11
	s_add_u32 s4, s6, s12
	s_addc_u32 s5, s7, s13
	v_lshl_add_u64 v[130:131], s[4:5], 0, v[0:1]
	v_lshlrev_b32_e32 v0, 4, v6
	v_and_b32_e32 v0, 0xc0, v0
	s_lshl_b32 s4, s24, 8
	s_sub_i32 s24, 0x1fff, s4
	v_lshl_or_b32 v0, v135, 8, v0
	v_readlane_b32 s4, v254, 6
	v_lshlrev_b32_e32 v2, 1, v6
	v_lshlrev_b32_e32 v4, 10, v135
	v_add_u32_e32 v140, s4, v0
	v_readlane_b32 s4, v254, 7
	v_lshlrev_b32_e32 v3, 4, v134
	v_mov_b32_e32 v14, v1
	v_add_u32_e32 v142, s4, v0
	v_readlane_b32 s4, v254, 8
	v_mov_b32_e32 v15, v1
	v_add3_u32 v138, 0, v4, v3
	v_add_u32_e32 v143, s4, v0
	v_readlane_b32 s4, v254, 9
	s_lshl_b32 s6, s16, 2
	s_waitcnt vmcnt(0) lgkmcnt(0)
	s_barrier
	v_and_or_b32 v141, v2, 32, v7
	v_add_u32_e32 v144, s4, v0
	v_readlane_b32 s4, v254, 10
	v_add_u32_e32 v156, s27, v0
	v_add_u32_e32 v174, s51, v0
	v_add_u32_e32 v145, s4, v0
	v_readlane_b32 s4, v254, 11
	v_add_u32_e32 v175, s33, v0
	v_add_u32_e32 v176, s26, v0
	v_add_u32_e32 v146, s4, v0
	v_readlane_b32 s4, v254, 12
	v_mov_b32_e32 v2, v1
	v_mov_b32_e32 v3, v1
	v_add_u32_e32 v147, s4, v0
	v_readlane_b32 s4, v254, 13
	v_mov_b32_e32 v4, v1
	v_mov_b32_e32 v6, v1
	v_add_u32_e32 v148, s4, v0
	v_readlane_b32 s4, v254, 14
	v_mov_b32_e32 v7, v1
	v_mov_b32_e32 v8, v1
	v_add_u32_e32 v149, s4, v0
	v_readlane_b32 s4, v254, 15
	v_mov_b32_e32 v9, v1
	v_mov_b32_e32 v10, v1
	v_add_u32_e32 v150, s4, v0
	v_readlane_b32 s4, v254, 16
	v_mov_b32_e32 v11, v1
	v_mov_b32_e32 v12, v1
	v_add_u32_e32 v151, s4, v0
	v_readlane_b32 s4, v254, 17
	v_mov_b32_e32 v13, v1
	s_add_i32 s22, s6, 0
	v_add_u32_e32 v152, s4, v0
	v_readlane_b32 s4, v254, 18
	s_addk_i32 s25, 0xff40
	s_mov_b32 s19, 1
	v_add_u32_e32 v153, s4, v0
	v_readlane_b32 s4, v254, 19
	v_cmp_gt_u32_e64 s[0:1], 32, v132
	s_or_b32 s21, s14, 30
	v_add_u32_e32 v154, s4, v0
	v_readlane_b32 s4, v254, 20
	s_add_i32 s22, s22, 0x14800
	s_mov_b32 s23, 0
	v_add_u32_e32 v155, s4, v0
	v_readlane_b32 s4, v255, 57
	v_cmp_eq_u32_e64 s[6:7], 0, v132
	v_or_b32_e32 v139, s25, v134
	v_add_u32_e32 v157, s4, v0
	v_readlane_b32 s4, v255, 58
	s_add_i32 s25, s18, 0xc000
	v_mov_b32_e32 v177, 0
	v_add_u32_e32 v162, s4, v0
	v_readlane_b32 s4, v255, 59
	s_mov_b32 s28, 0
	s_waitcnt vmcnt(0)
	v_add_u32_e32 v163, s4, v0
	v_readlane_b32 s4, v255, 60
	s_nop 1
	v_add_u32_e32 v164, s4, v0
	v_readlane_b32 s4, v255, 61
	s_nop 1
	v_add_u32_e32 v165, s4, v0
	v_readlane_b32 s4, v255, 62
	s_nop 1
	v_add_u32_e32 v166, s4, v0
	v_readlane_b32 s4, v255, 63
	s_nop 1
	v_add_u32_e32 v167, s4, v0
	v_readlane_b32 s4, v254, 0
	s_nop 1
	v_add_u32_e32 v168, s4, v0
	v_readlane_b32 s4, v254, 1
	s_nop 1
	v_add_u32_e32 v169, s4, v0
	v_readlane_b32 s4, v254, 2
	s_nop 1
	v_add_u32_e32 v170, s4, v0
	v_readlane_b32 s4, v254, 3
	s_nop 1
	v_add_u32_e32 v171, s4, v0
	v_readlane_b32 s4, v254, 4
	s_nop 1
	v_add_u32_e32 v172, s4, v0
	v_readlane_b32 s4, v254, 5
	s_nop 1
	v_add_u32_e32 v173, s4, v0
	v_mov_b32_e32 v0, v1
	v_mov_b64_e32 v[64:65], v[14:15]
	v_mov_b64_e32 v[48:49], v[14:15]
	v_mov_b64_e32 v[32:33], v[14:15]
	v_mov_b64_e32 v[62:63], v[12:13]
	v_mov_b64_e32 v[60:61], v[10:11]
	v_mov_b64_e32 v[58:59], v[8:9]
	v_mov_b64_e32 v[56:57], v[6:7]
	v_mov_b64_e32 v[54:55], v[4:5]
	v_mov_b64_e32 v[52:53], v[2:3]
	v_mov_b64_e32 v[50:51], v[0:1]
	v_mov_b64_e32 v[46:47], v[12:13]
	v_mov_b64_e32 v[44:45], v[10:11]
	v_mov_b64_e32 v[42:43], v[8:9]
	v_mov_b64_e32 v[40:41], v[6:7]
	v_mov_b64_e32 v[38:39], v[4:5]
	v_mov_b64_e32 v[36:37], v[2:3]
	v_mov_b64_e32 v[34:35], v[0:1]
	v_mov_b64_e32 v[30:31], v[12:13]
	v_mov_b64_e32 v[28:29], v[10:11]
	v_mov_b64_e32 v[26:27], v[8:9]
	v_mov_b64_e32 v[24:25], v[6:7]
	v_mov_b64_e32 v[22:23], v[4:5]
	v_mov_b64_e32 v[20:21], v[2:3]
	v_mov_b64_e32 v[18:19], v[0:1]
	v_mov_b64_e32 v[16:17], v[14:15]
	v_mov_b64_e32 v[14:15], v[12:13]
	v_mov_b64_e32 v[12:13], v[10:11]
	v_mov_b64_e32 v[10:11], v[8:9]
	v_mov_b64_e32 v[8:9], v[6:7]
	v_mov_b64_e32 v[6:7], v[4:5]
	v_mov_b64_e32 v[4:5], v[2:3]
	v_mov_b64_e32 v[2:3], v[0:1]
	s_cmp_eq_u32 s20, s28
	s_cbranch_scc0 .LBB0_269
